# P7 rewritten by hand: w_router staged in LDS with padded conflict-free layout, batched DPP transposing reduction for router logits, next-row prefetch
# speedup vs baseline: 1.0712x; 1.0712x over previous
; DEVINL float bflo(unsigned u) { return __uint_as_float(u << 16); }
; DEVINL float bfhi(unsigned u) { return __uint_as_float(u & 0xffff0000u); }
; DEVINL int otid() { int t = threadIdx.x; asm volatile("" : "+v"(t)); return t; }
; DEVINL void phase7(const Params& p) {
;   char* ws = p.ws;
;   const int tid = otid();
;   const int lane = tid & 63;
;   const int gw = blockIdx.x * 8 + (tid >> 6), nw = gridDim.x * 8;
;   for (int row = gw; row < T_; row += nw) {
;     const u16* r1 = (const u16*)(ws + O_R1) + (long)row * 2048;
;     float4 v[8];
;     float sum = 0.f;
; #pragma unroll
;     for (int i = 0; i < 8; ++i) {
;       const uint2 q = *(const uint2*)(r1 + i * 256 + lane * 4);
;       v[i] = make_float4(bflo(q.x), bfhi(q.x), bflo(q.y), bfhi(q.y));
;       sum += v[i].x + v[i].y + v[i].z + v[i].w;
;     }
;     ...
;     float lg[16];
; #pragma unroll
;     for (int e = 0; e < 16; ++e) lg[e] = 0.f;
; #pragma unroll
;     for (int i = 0; i < 8; ++i) {
;       const int c = i * 256 + lane * 4;
;       float4 gq = *(const float4*)(p.ln1_g + c);
;       float4 bq = *(const float4*)(p.ln1_b + c);
.LBB0_737:
	s_or_b64 exec, exec, s[0:1]
	s_waitcnt lgkmcnt(0)
	v_mov_b32_e32 v1, v189
	s_barrier
	v_and_b32_e32 v0, 63, v189
	v_lshrrev_b32_e32 v8, 6, v189
	v_lshlrev_b32_e32 v9, 4, v189
	v_readfirstlane_b32 s4, v8
	s_lshl_b32 s5, s2, 3
	s_add_u32 s4, s4, s5
	s_lshl_b32 s5, s94, 3
	v_lshlrev_b32_e32 v6, 4, v0
	v_add_u32_e32 v7, 0x1000, v6
	global_load_dwordx4 v[90:93], v6, s[74:75] offset:0
	global_load_dwordx4 v[94:97], v6, s[74:75] offset:1024
	global_load_dwordx4 v[98:101], v6, s[74:75] offset:2048
	global_load_dwordx4 v[102:105], v6, s[74:75] offset:3072
	global_load_dwordx4 v[106:109], v7, s[74:75] offset:0
	global_load_dwordx4 v[110:113], v7, s[74:75] offset:1024
	global_load_dwordx4 v[114:117], v7, s[74:75] offset:2048
	global_load_dwordx4 v[118:121], v7, s[74:75] offset:3072
	global_load_dwordx4 v[122:125], v6, s[76:77] offset:0
	global_load_dwordx4 v[126:129], v6, s[76:77] offset:1024
	global_load_dwordx4 v[130:133], v6, s[76:77] offset:2048
	global_load_dwordx4 v[134:137], v6, s[76:77] offset:3072
	global_load_dwordx4 v[138:141], v7, s[76:77] offset:0
	global_load_dwordx4 v[142:145], v7, s[76:77] offset:1024
	global_load_dwordx4 v[146:149], v7, s[76:77] offset:2048
	global_load_dwordx4 v[150:153], v7, s[76:77] offset:3072
	global_load_dwordx4 v[10:13], v9, s[78:79]
	v_add_u32_e32 v9, 0x2000, v9
	global_load_dwordx4 v[14:17], v9, s[78:79]
	v_add_u32_e32 v9, 0x2000, v9
	global_load_dwordx4 v[18:21], v9, s[78:79]
	v_add_u32_e32 v9, 0x2000, v9
	global_load_dwordx4 v[22:25], v9, s[78:79]
	v_add_u32_e32 v9, 0x2000, v9
	global_load_dwordx4 v[26:29], v9, s[78:79]
	v_add_u32_e32 v9, 0x2000, v9
	global_load_dwordx4 v[30:33], v9, s[78:79]
	v_add_u32_e32 v9, 0x2000, v9
	global_load_dwordx4 v[34:37], v9, s[78:79]
	v_add_u32_e32 v9, 0x2000, v9
	global_load_dwordx4 v[38:41], v9, s[78:79]
	v_add_u32_e32 v9, 0x2000, v9
	global_load_dwordx4 v[42:45], v9, s[78:79]
	v_add_u32_e32 v9, 0x2000, v9
	global_load_dwordx4 v[46:49], v9, s[78:79]
	v_add_u32_e32 v9, 0x2000, v9
	global_load_dwordx4 v[50:53], v9, s[78:79]
	v_add_u32_e32 v9, 0x2000, v9
	global_load_dwordx4 v[54:57], v9, s[78:79]
	v_add_u32_e32 v9, 0x2000, v9
	global_load_dwordx4 v[58:61], v9, s[78:79]
	v_add_u32_e32 v9, 0x2000, v9
	global_load_dwordx4 v[62:65], v9, s[78:79]
	v_add_u32_e32 v9, 0x2000, v9
	global_load_dwordx4 v[66:69], v9, s[78:79]
	v_add_u32_e32 v9, 0x2000, v9
	global_load_dwordx4 v[70:73], v9, s[78:79]
	v_lshrrev_b32_e32 v8, 4, v189
	v_and_b32_e32 v6, 15, v189
	v_mul_u32_u24_e32 v8, 0x110, v8
	v_lshl_add_u32 v8, v6, 4, v8
	v_add_u32_e32 v8, 16, v8
	v_add_u32_e32 v7, 0x11000, v8
	s_waitcnt vmcnt(15)
	ds_write_b128 v8, v[10:13] offset:0
	s_waitcnt vmcnt(14)
	ds_write_b128 v8, v[14:17] offset:8704
	s_waitcnt vmcnt(13)
	ds_write_b128 v8, v[18:21] offset:17408
	s_waitcnt vmcnt(12)
	ds_write_b128 v8, v[22:25] offset:26112
	s_waitcnt vmcnt(11)
	ds_write_b128 v8, v[26:29] offset:34816
	s_waitcnt vmcnt(10)
	ds_write_b128 v8, v[30:33] offset:43520
	s_waitcnt vmcnt(9)
	ds_write_b128 v8, v[34:37] offset:52224
	s_waitcnt vmcnt(8)
	ds_write_b128 v8, v[38:41] offset:60928
	s_waitcnt vmcnt(7)
	ds_write_b128 v7, v[42:45] offset:0
	s_waitcnt vmcnt(6)
	ds_write_b128 v7, v[46:49] offset:8704
	s_waitcnt vmcnt(5)
	ds_write_b128 v7, v[50:53] offset:17408
	s_waitcnt vmcnt(4)
	ds_write_b128 v7, v[54:57] offset:26112
	s_waitcnt vmcnt(3)
	ds_write_b128 v7, v[58:61] offset:34816
	s_waitcnt vmcnt(2)
	ds_write_b128 v7, v[62:65] offset:43520
	s_waitcnt vmcnt(1)
	ds_write_b128 v7, v[66:69] offset:52224
	s_waitcnt vmcnt(0)
	ds_write_b128 v7, v[70:73] offset:60928
	v_lshlrev_b32_e32 v1, 3, v0
	v_mul_u32_u24_e32 v2, 0x110, v0
	v_add_u32_e32 v2, 16, v2
	v_add_u32_e32 v3, 0x11000, v2
	v_lshlrev_b32_e32 v4, 2, v0
	v_lshlrev_b32_e32 v5, 14, v0
	v_xor_b32_e32 v6, 16, v0
	v_lshlrev_b32_e32 v6, 2, v6
	v_xor_b32_e32 v7, 32, v0
	v_lshlrev_b32_e32 v7, 2, v7
	v_mov_b32_e32 v186, 0x3727c5ac
	v_mov_b32_e32 v187, -1
	s_mov_b32 s14, 0xaaaaaaaa
	s_mov_b32 s15, 0xaaaaaaaa
	s_mov_b32 s16, 0xcccccccc
	s_mov_b32 s17, 0xcccccccc
	s_mov_b32 s22, 0x3a000000
	s_waitcnt lgkmcnt(0)
	s_barrier
	s_cmp_ge_u32 s4, 0x2000
	s_cbranch_scc1 .Lp7_end
	s_lshl_b32 s0, s4, 12
	s_add_u32 s6, s92, s0
	s_addc_u32 s7, s93, 0
	global_load_dwordx2 v[154:155], v1, s[6:7] offset:0
	global_load_dwordx2 v[156:157], v1, s[6:7] offset:512
	global_load_dwordx2 v[158:159], v1, s[6:7] offset:1024
	global_load_dwordx2 v[160:161], v1, s[6:7] offset:1536
	global_load_dwordx2 v[162:163], v1, s[6:7] offset:2048
	global_load_dwordx2 v[164:165], v1, s[6:7] offset:2560
	global_load_dwordx2 v[166:167], v1, s[6:7] offset:3072
	global_load_dwordx2 v[168:169], v1, s[6:7] offset:3584
	s_waitcnt vmcnt(0)
	s_branch .Lp7_row_body
.Lp7_row:
	s_waitcnt vmcnt(10)
; DEVINL float bflo(unsigned u) { return __uint_as_float(u << 16); }
; DEVINL float bfhi(unsigned u) { return __uint_as_float(u & 0xffff0000u); }
; DEVINL void phase7(const Params& p) {
;     ...
;   for (int row = gw; row < T_; row += nw) {
;     const u16* r1 = (const u16*)(ws + O_R1) + (long)row * 2048;
;     float4 v[8];
;     float sum = 0.f;
; #pragma unroll
;     for (int i = 0; i < 8; ++i) {
;       const uint2 q = *(const uint2*)(r1 + i * 256 + lane * 4);
;       v[i] = make_float4(bflo(q.x), bfhi(q.x), bflo(q.y), bfhi(q.y));
;       sum += v[i].x + v[i].y + v[i].z + v[i].w;
;     }
;     const float mu = allred64(sum) * (1.f / 2048.f);
;     float sq = 0.f;
; #pragma unroll
;     for (int i = 0; i < 8; ++i) {
;       v[i].x -= mu; v[i].y -= mu; v[i].z -= mu; v[i].w -= mu;
;       sq += v[i].x * v[i].x + v[i].y * v[i].y + v[i].z * v[i].z + v[i].w * v[i].w;
;     }
;     const float rstd = rsqrtf(allred64(sq) * (1.f / 2048.f) + 1e-5f);
.Lp7_row_body:
	v_lshlrev_b32_e32 v10, 16, v154
	v_and_b32_e32 v11, 0xffff0000, v154
	v_lshlrev_b32_e32 v12, 16, v155
	v_and_b32_e32 v13, 0xffff0000, v155
	v_lshlrev_b32_e32 v14, 16, v156
	v_and_b32_e32 v15, 0xffff0000, v156
	v_lshlrev_b32_e32 v16, 16, v157
	v_and_b32_e32 v17, 0xffff0000, v157
	v_lshlrev_b32_e32 v18, 16, v158
	v_and_b32_e32 v19, 0xffff0000, v158
	v_lshlrev_b32_e32 v20, 16, v159
	v_and_b32_e32 v21, 0xffff0000, v159
	v_lshlrev_b32_e32 v22, 16, v160
	v_and_b32_e32 v23, 0xffff0000, v160
	v_lshlrev_b32_e32 v24, 16, v161
	v_and_b32_e32 v25, 0xffff0000, v161
	v_lshlrev_b32_e32 v26, 16, v162
	v_and_b32_e32 v27, 0xffff0000, v162
	v_lshlrev_b32_e32 v28, 16, v163
	v_and_b32_e32 v29, 0xffff0000, v163
	v_lshlrev_b32_e32 v30, 16, v164
	v_and_b32_e32 v31, 0xffff0000, v164
	v_lshlrev_b32_e32 v32, 16, v165
	v_and_b32_e32 v33, 0xffff0000, v165
	v_lshlrev_b32_e32 v34, 16, v166
	v_and_b32_e32 v35, 0xffff0000, v166
	v_lshlrev_b32_e32 v36, 16, v167
	v_and_b32_e32 v37, 0xffff0000, v167
	v_lshlrev_b32_e32 v38, 16, v168
	v_and_b32_e32 v39, 0xffff0000, v168
	v_lshlrev_b32_e32 v40, 16, v169
	v_and_b32_e32 v41, 0xffff0000, v169
	s_add_u32 s20, s4, s5
	s_cmp_lt_u32 s20, 0x2000
	s_cselect_b32 s20, s20, s4
	s_lshl_b32 s0, s20, 12
	s_add_u32 s6, s92, s0
	s_addc_u32 s7, s93, 0
	global_load_dwordx2 v[154:155], v1, s[6:7] offset:0
	global_load_dwordx2 v[156:157], v1, s[6:7] offset:512
	global_load_dwordx2 v[158:159], v1, s[6:7] offset:1024
	global_load_dwordx2 v[160:161], v1, s[6:7] offset:1536
	global_load_dwordx2 v[162:163], v1, s[6:7] offset:2048
	global_load_dwordx2 v[164:165], v1, s[6:7] offset:2560
	global_load_dwordx2 v[166:167], v1, s[6:7] offset:3072
	global_load_dwordx2 v[168:169], v1, s[6:7] offset:3584
	ds_read_b128 v[58:61], v2 offset:0
	ds_read_b128 v[62:65], v2 offset:16
	ds_read_b128 v[66:69], v2 offset:32
	ds_read_b128 v[70:73], v2 offset:48
	v_add_f32_e32 v8, v10, v11
	v_add_f32_e32 v8, v8, v12
	v_add_f32_e32 v8, v8, v13
	v_add_f32_e32 v9, v14, v15
	v_add_f32_e32 v9, v9, v16
	v_add_f32_e32 v9, v9, v17
	v_add_f32_e32 v8, v8, v9
	v_add_f32_e32 v9, v18, v19
	v_add_f32_e32 v9, v9, v20
	v_add_f32_e32 v9, v9, v21
	v_add_f32_e32 v8, v8, v9
	v_add_f32_e32 v9, v22, v23
	v_add_f32_e32 v9, v9, v24
	v_add_f32_e32 v9, v9, v25
	v_add_f32_e32 v8, v8, v9
	v_add_f32_e32 v9, v26, v27
	v_add_f32_e32 v9, v9, v28
	v_add_f32_e32 v9, v9, v29
	v_add_f32_e32 v8, v8, v9
	v_add_f32_e32 v9, v30, v31
	v_add_f32_e32 v9, v9, v32
	v_add_f32_e32 v9, v9, v33
	v_add_f32_e32 v8, v8, v9
	v_add_f32_e32 v9, v34, v35
	v_add_f32_e32 v9, v9, v36
	v_add_f32_e32 v9, v9, v37
	v_add_f32_e32 v8, v8, v9
	v_add_f32_e32 v9, v38, v39
	v_add_f32_e32 v9, v9, v40
	v_add_f32_e32 v9, v9, v41
	v_add_f32_e32 v8, v8, v9
	s_nop 1
	v_add_f32_dpp v8, v8, v8 quad_perm:[1,0,3,2] row_mask:0xf bank_mask:0xf bound_ctrl:1
	s_nop 1
	v_add_f32_dpp v8, v8, v8 quad_perm:[2,3,0,1] row_mask:0xf bank_mask:0xf bound_ctrl:1
	s_nop 1
	v_add_f32_dpp v8, v8, v8 row_half_mirror row_mask:0xf bank_mask:0xf bound_ctrl:1
	s_nop 1
	v_add_f32_dpp v8, v8, v8 row_mirror row_mask:0xf bank_mask:0xf bound_ctrl:1
	v_mov_b32_e32 v9, 0
	s_nop 1
	v_mov_b32_dpp v9, v8 row_bcast:15 row_mask:0xa bank_mask:0xf
	v_add_f32_e32 v8, v8, v9
	s_nop 1
	v_mov_b32_dpp v9, v8 row_bcast:31 row_mask:0xc bank_mask:0xf
	v_add_f32_e32 v8, v8, v9
	s_nop 0
	v_readlane_b32 s21, v8, 63
	s_nop 1
	v_mov_b32_e32 v9, s21
	v_mul_f32_e32 v9, 0x3a000000, v9
	v_sub_f32_e32 v10, v10, v9
	v_sub_f32_e32 v11, v11, v9
	v_sub_f32_e32 v12, v12, v9
	v_sub_f32_e32 v13, v13, v9
	v_sub_f32_e32 v14, v14, v9
	v_sub_f32_e32 v15, v15, v9
	v_sub_f32_e32 v16, v16, v9
	v_sub_f32_e32 v17, v17, v9
	v_sub_f32_e32 v18, v18, v9
	v_sub_f32_e32 v19, v19, v9
	v_sub_f32_e32 v20, v20, v9
	v_sub_f32_e32 v21, v21, v9
	v_sub_f32_e32 v22, v22, v9
	v_sub_f32_e32 v23, v23, v9
	v_sub_f32_e32 v24, v24, v9
	v_sub_f32_e32 v25, v25, v9
	v_sub_f32_e32 v26, v26, v9
	v_sub_f32_e32 v27, v27, v9
	v_sub_f32_e32 v28, v28, v9
	v_sub_f32_e32 v29, v29, v9
	v_sub_f32_e32 v30, v30, v9
	v_sub_f32_e32 v31, v31, v9
	v_sub_f32_e32 v32, v32, v9
	v_sub_f32_e32 v33, v33, v9
	v_sub_f32_e32 v34, v34, v9
	v_sub_f32_e32 v35, v35, v9
	v_sub_f32_e32 v36, v36, v9
	v_sub_f32_e32 v37, v37, v9
	v_sub_f32_e32 v38, v38, v9
	v_sub_f32_e32 v39, v39, v9
	v_sub_f32_e32 v40, v40, v9
	v_sub_f32_e32 v41, v41, v9
	v_mul_f32_e32 v8, v10, v10
	v_fmac_f32_e32 v8, v11, v11
	v_fmac_f32_e32 v8, v12, v12
	v_fmac_f32_e32 v8, v13, v13
	v_mul_f32_e32 v9, v14, v14
	v_fmac_f32_e32 v9, v15, v15
	v_fmac_f32_e32 v9, v16, v16
	v_fmac_f32_e32 v9, v17, v17
	v_add_f32_e32 v8, v8, v9
	v_mul_f32_e32 v9, v18, v18
	v_fmac_f32_e32 v9, v19, v19
	v_fmac_f32_e32 v9, v20, v20
	v_fmac_f32_e32 v9, v21, v21
	v_add_f32_e32 v8, v8, v9
	v_mul_f32_e32 v9, v22, v22
	v_fmac_f32_e32 v9, v23, v23
	v_fmac_f32_e32 v9, v24, v24
	v_fmac_f32_e32 v9, v25, v25
	v_add_f32_e32 v8, v8, v9
	v_mul_f32_e32 v9, v26, v26
	v_fmac_f32_e32 v9, v27, v27
	v_fmac_f32_e32 v9, v28, v28
	v_fmac_f32_e32 v9, v29, v29
	v_add_f32_e32 v8, v8, v9
	v_mul_f32_e32 v9, v30, v30
	v_fmac_f32_e32 v9, v31, v31
	v_fmac_f32_e32 v9, v32, v32
	v_fmac_f32_e32 v9, v33, v33
	v_add_f32_e32 v8, v8, v9
	v_mul_f32_e32 v9, v34, v34
	v_fmac_f32_e32 v9, v35, v35
	v_fmac_f32_e32 v9, v36, v36
	v_fmac_f32_e32 v9, v37, v37
	v_add_f32_e32 v8, v8, v9
	v_mul_f32_e32 v9, v38, v38
	v_fmac_f32_e32 v9, v39, v39
	v_fmac_f32_e32 v9, v40, v40
	v_fmac_f32_e32 v9, v41, v41
	v_add_f32_e32 v8, v8, v9
	s_nop 1
	v_add_f32_dpp v8, v8, v8 quad_perm:[1,0,3,2] row_mask:0xf bank_mask:0xf bound_ctrl:1
	s_nop 1
	v_add_f32_dpp v8, v8, v8 quad_perm:[2,3,0,1] row_mask:0xf bank_mask:0xf bound_ctrl:1
	s_nop 1
	v_add_f32_dpp v8, v8, v8 row_half_mirror row_mask:0xf bank_mask:0xf bound_ctrl:1
; DEVINL void phase7(const Params& p) {
;     ...
;     const float rstd = rsqrtf(allred64(sq) * (1.f / 2048.f) + 1e-5f);
;     float lg[16];
; #pragma unroll
;     for (int e = 0; e < 16; ++e) lg[e] = 0.f;
; #pragma unroll
;     for (int i = 0; i < 8; ++i) {
;       const int c = i * 256 + lane * 4;
;       float4 gq = *(const float4*)(p.ln1_g + c);
;       float4 bq = *(const float4*)(p.ln1_b + c);
;       float h0 = v[i].x * rstd * gq.x + bq.x, h1 = v[i].y * rstd * gq.y + bq.y;
;       float h2 = v[i].z * rstd * gq.z + bq.z, h3 = v[i].w * rstd * gq.w + bq.w;
;       *(uint2*)((u16*)(ws + O_HBF) + (long)row * 2048 + c) = make_uint2(pk2(h0, h1), pk2(h2, h3));
;       const float hh[4] = {h0, h1, h2, h3};
; #pragma unroll
;       for (int q = 0; q < 4; ++q) {
;         const float4* wr = (const float4*)(p.w_router + (long)(c + q) * 16);
; #pragma unroll
;         for (int e4 = 0; e4 < 4; ++e4) {
;           float4 w = wr[e4];
;           lg[e4 * 4 + 0] += hh[q] * w.x; lg[e4 * 4 + 1] += hh[q] * w.y;
;           lg[e4 * 4 + 2] += hh[q] * w.z; lg[e4 * 4 + 3] += hh[q] * w.w;
;         }
;       }
	s_nop 1
	v_add_f32_dpp v8, v8, v8 row_mirror row_mask:0xf bank_mask:0xf bound_ctrl:1
	v_mov_b32_e32 v9, 0
	s_nop 1
	v_mov_b32_dpp v9, v8 row_bcast:15 row_mask:0xa bank_mask:0xf
	v_add_f32_e32 v8, v8, v9
	s_nop 1
	v_mov_b32_dpp v9, v8 row_bcast:31 row_mask:0xc bank_mask:0xf
	v_add_f32_e32 v8, v8, v9
	s_nop 0
	v_readlane_b32 s21, v8, 63
	s_nop 1
	v_mov_b32_e32 v9, s21
	v_fma_f32 v9, v9, s22, v186
	v_rsq_f32_e32 v9, v9
	s_nop 0
	v_mul_f32_e32 v10, v10, v9
	v_fma_f32 v10, v10, v90, v122
	v_mul_f32_e32 v11, v11, v9
	v_fma_f32 v11, v11, v91, v123
	v_mul_f32_e32 v12, v12, v9
	v_fma_f32 v12, v12, v92, v124
	v_mul_f32_e32 v13, v13, v9
	v_fma_f32 v13, v13, v93, v125
	v_mul_f32_e32 v14, v14, v9
	v_fma_f32 v14, v14, v94, v126
	v_mul_f32_e32 v15, v15, v9
	v_fma_f32 v15, v15, v95, v127
	v_mul_f32_e32 v16, v16, v9
	v_fma_f32 v16, v16, v96, v128
	v_mul_f32_e32 v17, v17, v9
	v_fma_f32 v17, v17, v97, v129
	v_mul_f32_e32 v18, v18, v9
	v_fma_f32 v18, v18, v98, v130
	v_mul_f32_e32 v19, v19, v9
	v_fma_f32 v19, v19, v99, v131
	v_mul_f32_e32 v20, v20, v9
	v_fma_f32 v20, v20, v100, v132
	v_mul_f32_e32 v21, v21, v9
	v_fma_f32 v21, v21, v101, v133
	v_mul_f32_e32 v22, v22, v9
	v_fma_f32 v22, v22, v102, v134
	v_mul_f32_e32 v23, v23, v9
	v_fma_f32 v23, v23, v103, v135
	v_mul_f32_e32 v24, v24, v9
	v_fma_f32 v24, v24, v104, v136
	v_mul_f32_e32 v25, v25, v9
	v_fma_f32 v25, v25, v105, v137
	v_mul_f32_e32 v26, v26, v9
	v_fma_f32 v26, v26, v106, v138
	v_mul_f32_e32 v27, v27, v9
	v_fma_f32 v27, v27, v107, v139
	v_mul_f32_e32 v28, v28, v9
	v_fma_f32 v28, v28, v108, v140
	v_mul_f32_e32 v29, v29, v9
	v_fma_f32 v29, v29, v109, v141
	v_mul_f32_e32 v30, v30, v9
	v_fma_f32 v30, v30, v110, v142
	v_mul_f32_e32 v31, v31, v9
	v_fma_f32 v31, v31, v111, v143
	v_mul_f32_e32 v32, v32, v9
	v_fma_f32 v32, v32, v112, v144
	v_mul_f32_e32 v33, v33, v9
	v_fma_f32 v33, v33, v113, v145
	v_mul_f32_e32 v34, v34, v9
	v_fma_f32 v34, v34, v114, v146
	v_mul_f32_e32 v35, v35, v9
	v_fma_f32 v35, v35, v115, v147
	v_mul_f32_e32 v36, v36, v9
	v_fma_f32 v36, v36, v116, v148
	v_mul_f32_e32 v37, v37, v9
	v_fma_f32 v37, v37, v117, v149
	v_mul_f32_e32 v38, v38, v9
	v_fma_f32 v38, v38, v118, v150
	v_mul_f32_e32 v39, v39, v9
	v_fma_f32 v39, v39, v119, v151
	v_mul_f32_e32 v40, v40, v9
	v_fma_f32 v40, v40, v120, v152
	v_mul_f32_e32 v41, v41, v9
	v_fma_f32 v41, v41, v121, v153
	v_cvt_pk_bf16_f32 v170, v10, v11
	v_cvt_pk_bf16_f32 v171, v12, v13
	v_cvt_pk_bf16_f32 v172, v14, v15
	v_cvt_pk_bf16_f32 v173, v16, v17
	v_cvt_pk_bf16_f32 v174, v18, v19
	v_cvt_pk_bf16_f32 v175, v20, v21
	v_cvt_pk_bf16_f32 v176, v22, v23
	v_cvt_pk_bf16_f32 v177, v24, v25
	v_cvt_pk_bf16_f32 v178, v26, v27
	v_cvt_pk_bf16_f32 v179, v28, v29
	v_cvt_pk_bf16_f32 v180, v30, v31
	v_cvt_pk_bf16_f32 v181, v32, v33
	v_cvt_pk_bf16_f32 v182, v34, v35
	v_cvt_pk_bf16_f32 v183, v36, v37
	v_cvt_pk_bf16_f32 v184, v38, v39
	v_cvt_pk_bf16_f32 v185, v40, v41
	s_lshl_b32 s0, s4, 12
	s_add_u32 s8, s92, s0
	s_addc_u32 s9, s93, 0
	s_add_u32 s8, s8, 0x17400000
	s_addc_u32 s9, s9, 0
	global_store_dwordx2 v1, v[170:171], s[8:9] offset:0
	global_store_dwordx2 v1, v[172:173], s[8:9] offset:512
	global_store_dwordx2 v1, v[174:175], s[8:9] offset:1024
	global_store_dwordx2 v1, v[176:177], s[8:9] offset:1536
	global_store_dwordx2 v1, v[178:179], s[8:9] offset:2048
	global_store_dwordx2 v1, v[180:181], s[8:9] offset:2560
	global_store_dwordx2 v1, v[182:183], s[8:9] offset:3072
	global_store_dwordx2 v1, v[184:185], s[8:9] offset:3584
	v_mov_b32_e32 v42, 0
	v_mov_b32_e32 v43, 0
	v_mov_b32_e32 v44, 0
	v_mov_b32_e32 v45, 0
	v_mov_b32_e32 v46, 0
	v_mov_b32_e32 v47, 0
	v_mov_b32_e32 v48, 0
	v_mov_b32_e32 v49, 0
	v_mov_b32_e32 v50, 0
	v_mov_b32_e32 v51, 0
	v_mov_b32_e32 v52, 0
	v_mov_b32_e32 v53, 0
	v_mov_b32_e32 v54, 0
	v_mov_b32_e32 v55, 0
	v_mov_b32_e32 v56, 0
	v_mov_b32_e32 v57, 0
	ds_read_b128 v[74:77], v2 offset:64
	ds_read_b128 v[78:81], v2 offset:80
	ds_read_b128 v[82:85], v2 offset:96
	ds_read_b128 v[86:89], v2 offset:112
	s_waitcnt lgkmcnt(4)
	v_fmac_f32_e32 v42, v10, v58
	v_fmac_f32_e32 v43, v10, v59
	v_fmac_f32_e32 v44, v10, v60
	v_fmac_f32_e32 v45, v10, v61
	v_fmac_f32_e32 v46, v10, v62
	v_fmac_f32_e32 v47, v10, v63
	v_fmac_f32_e32 v48, v10, v64
	v_fmac_f32_e32 v49, v10, v65
	v_fmac_f32_e32 v50, v10, v66
	v_fmac_f32_e32 v51, v10, v67
	v_fmac_f32_e32 v52, v10, v68
	v_fmac_f32_e32 v53, v10, v69
	v_fmac_f32_e32 v54, v10, v70
	v_fmac_f32_e32 v55, v10, v71
	v_fmac_f32_e32 v56, v10, v72
	v_fmac_f32_e32 v57, v10, v73
	ds_read_b128 v[58:61], v2 offset:128
	ds_read_b128 v[62:65], v2 offset:144
	ds_read_b128 v[66:69], v2 offset:160
	ds_read_b128 v[70:73], v2 offset:176
	s_waitcnt lgkmcnt(4)
	v_fmac_f32_e32 v42, v11, v74
	v_fmac_f32_e32 v43, v11, v75
	v_fmac_f32_e32 v44, v11, v76
	v_fmac_f32_e32 v45, v11, v77
	v_fmac_f32_e32 v46, v11, v78
	v_fmac_f32_e32 v47, v11, v79
	v_fmac_f32_e32 v48, v11, v80
	v_fmac_f32_e32 v49, v11, v81
	v_fmac_f32_e32 v50, v11, v82
	v_fmac_f32_e32 v51, v11, v83
	v_fmac_f32_e32 v52, v11, v84
	v_fmac_f32_e32 v53, v11, v85
	v_fmac_f32_e32 v54, v11, v86
	v_fmac_f32_e32 v55, v11, v87
	v_fmac_f32_e32 v56, v11, v88
	v_fmac_f32_e32 v57, v11, v89
	ds_read_b128 v[74:77], v2 offset:192
	ds_read_b128 v[78:81], v2 offset:208
	ds_read_b128 v[82:85], v2 offset:224
	ds_read_b128 v[86:89], v2 offset:240
	s_waitcnt lgkmcnt(4)
	v_fmac_f32_e32 v42, v12, v58
	v_fmac_f32_e32 v43, v12, v59
	v_fmac_f32_e32 v44, v12, v60
	v_fmac_f32_e32 v45, v12, v61
	v_fmac_f32_e32 v46, v12, v62
	v_fmac_f32_e32 v47, v12, v63
	v_fmac_f32_e32 v48, v12, v64
	v_fmac_f32_e32 v49, v12, v65
	v_fmac_f32_e32 v50, v12, v66
	v_fmac_f32_e32 v51, v12, v67
	v_fmac_f32_e32 v52, v12, v68
	v_fmac_f32_e32 v53, v12, v69
	v_fmac_f32_e32 v54, v12, v70
	v_fmac_f32_e32 v55, v12, v71
	v_fmac_f32_e32 v56, v12, v72
	v_fmac_f32_e32 v57, v12, v73
	ds_read_b128 v[58:61], v2 offset:17408
	ds_read_b128 v[62:65], v2 offset:17424
	ds_read_b128 v[66:69], v2 offset:17440
	ds_read_b128 v[70:73], v2 offset:17456
	s_waitcnt lgkmcnt(4)
; DEVINL void phase7(const Params& p) {
;     ...
; #pragma unroll
;       for (int q = 0; q < 4; ++q) {
;         const float4* wr = (const float4*)(p.w_router + (long)(c + q) * 16);
; #pragma unroll
;         for (int e4 = 0; e4 < 4; ++e4) {
;           float4 w = wr[e4];
;           lg[e4 * 4 + 0] += hh[q] * w.x; lg[e4 * 4 + 1] += hh[q] * w.y;
;           lg[e4 * 4 + 2] += hh[q] * w.z; lg[e4 * 4 + 3] += hh[q] * w.w;
;         }
;       }
	v_fmac_f32_e32 v42, v13, v74
	v_fmac_f32_e32 v43, v13, v75
	v_fmac_f32_e32 v44, v13, v76
	v_fmac_f32_e32 v45, v13, v77
	v_fmac_f32_e32 v46, v13, v78
	v_fmac_f32_e32 v47, v13, v79
	v_fmac_f32_e32 v48, v13, v80
	v_fmac_f32_e32 v49, v13, v81
	v_fmac_f32_e32 v50, v13, v82
	v_fmac_f32_e32 v51, v13, v83
	v_fmac_f32_e32 v52, v13, v84
	v_fmac_f32_e32 v53, v13, v85
	v_fmac_f32_e32 v54, v13, v86
	v_fmac_f32_e32 v55, v13, v87
	v_fmac_f32_e32 v56, v13, v88
	v_fmac_f32_e32 v57, v13, v89
	ds_read_b128 v[74:77], v2 offset:17472
	ds_read_b128 v[78:81], v2 offset:17488
	ds_read_b128 v[82:85], v2 offset:17504
	ds_read_b128 v[86:89], v2 offset:17520
	s_waitcnt lgkmcnt(4)
	v_fmac_f32_e32 v42, v14, v58
	v_fmac_f32_e32 v43, v14, v59
	v_fmac_f32_e32 v44, v14, v60
	v_fmac_f32_e32 v45, v14, v61
	v_fmac_f32_e32 v46, v14, v62
	v_fmac_f32_e32 v47, v14, v63
	v_fmac_f32_e32 v48, v14, v64
	v_fmac_f32_e32 v49, v14, v65
	v_fmac_f32_e32 v50, v14, v66
	v_fmac_f32_e32 v51, v14, v67
	v_fmac_f32_e32 v52, v14, v68
	v_fmac_f32_e32 v53, v14, v69
	v_fmac_f32_e32 v54, v14, v70
	v_fmac_f32_e32 v55, v14, v71
	v_fmac_f32_e32 v56, v14, v72
	v_fmac_f32_e32 v57, v14, v73
	ds_read_b128 v[58:61], v2 offset:17536
	ds_read_b128 v[62:65], v2 offset:17552
	ds_read_b128 v[66:69], v2 offset:17568
	ds_read_b128 v[70:73], v2 offset:17584
	s_waitcnt lgkmcnt(4)
	v_fmac_f32_e32 v42, v15, v74
	v_fmac_f32_e32 v43, v15, v75
	v_fmac_f32_e32 v44, v15, v76
	v_fmac_f32_e32 v45, v15, v77
	v_fmac_f32_e32 v46, v15, v78
	v_fmac_f32_e32 v47, v15, v79
	v_fmac_f32_e32 v48, v15, v80
	v_fmac_f32_e32 v49, v15, v81
	v_fmac_f32_e32 v50, v15, v82
	v_fmac_f32_e32 v51, v15, v83
	v_fmac_f32_e32 v52, v15, v84
	v_fmac_f32_e32 v53, v15, v85
	v_fmac_f32_e32 v54, v15, v86
	v_fmac_f32_e32 v55, v15, v87
	v_fmac_f32_e32 v56, v15, v88
	v_fmac_f32_e32 v57, v15, v89
	ds_read_b128 v[74:77], v2 offset:17600
	ds_read_b128 v[78:81], v2 offset:17616
	ds_read_b128 v[82:85], v2 offset:17632
	ds_read_b128 v[86:89], v2 offset:17648
	s_waitcnt lgkmcnt(4)
	v_fmac_f32_e32 v42, v16, v58
	v_fmac_f32_e32 v43, v16, v59
	v_fmac_f32_e32 v44, v16, v60
	v_fmac_f32_e32 v45, v16, v61
	v_fmac_f32_e32 v46, v16, v62
	v_fmac_f32_e32 v47, v16, v63
	v_fmac_f32_e32 v48, v16, v64
	v_fmac_f32_e32 v49, v16, v65
	v_fmac_f32_e32 v50, v16, v66
	v_fmac_f32_e32 v51, v16, v67
	v_fmac_f32_e32 v52, v16, v68
	v_fmac_f32_e32 v53, v16, v69
	v_fmac_f32_e32 v54, v16, v70
	v_fmac_f32_e32 v55, v16, v71
	v_fmac_f32_e32 v56, v16, v72
	v_fmac_f32_e32 v57, v16, v73
	ds_read_b128 v[58:61], v2 offset:34816
	ds_read_b128 v[62:65], v2 offset:34832
	ds_read_b128 v[66:69], v2 offset:34848
	ds_read_b128 v[70:73], v2 offset:34864
	s_waitcnt lgkmcnt(4)
	v_fmac_f32_e32 v42, v17, v74
	v_fmac_f32_e32 v43, v17, v75
	v_fmac_f32_e32 v44, v17, v76
	v_fmac_f32_e32 v45, v17, v77
	v_fmac_f32_e32 v46, v17, v78
	v_fmac_f32_e32 v47, v17, v79
	v_fmac_f32_e32 v48, v17, v80
	v_fmac_f32_e32 v49, v17, v81
	v_fmac_f32_e32 v50, v17, v82
	v_fmac_f32_e32 v51, v17, v83
	v_fmac_f32_e32 v52, v17, v84
	v_fmac_f32_e32 v53, v17, v85
	v_fmac_f32_e32 v54, v17, v86
	v_fmac_f32_e32 v55, v17, v87
	v_fmac_f32_e32 v56, v17, v88
	v_fmac_f32_e32 v57, v17, v89
	ds_read_b128 v[74:77], v2 offset:34880
	ds_read_b128 v[78:81], v2 offset:34896
	ds_read_b128 v[82:85], v2 offset:34912
	ds_read_b128 v[86:89], v2 offset:34928
	s_waitcnt lgkmcnt(4)
	v_fmac_f32_e32 v42, v18, v58
	v_fmac_f32_e32 v43, v18, v59
	v_fmac_f32_e32 v44, v18, v60
	v_fmac_f32_e32 v45, v18, v61
	v_fmac_f32_e32 v46, v18, v62
	v_fmac_f32_e32 v47, v18, v63
	v_fmac_f32_e32 v48, v18, v64
	v_fmac_f32_e32 v49, v18, v65
	v_fmac_f32_e32 v50, v18, v66
	v_fmac_f32_e32 v51, v18, v67
	v_fmac_f32_e32 v52, v18, v68
	v_fmac_f32_e32 v53, v18, v69
	v_fmac_f32_e32 v54, v18, v70
	v_fmac_f32_e32 v55, v18, v71
	v_fmac_f32_e32 v56, v18, v72
	v_fmac_f32_e32 v57, v18, v73
	ds_read_b128 v[58:61], v2 offset:34944
	ds_read_b128 v[62:65], v2 offset:34960
	ds_read_b128 v[66:69], v2 offset:34976
	ds_read_b128 v[70:73], v2 offset:34992
	s_waitcnt lgkmcnt(4)
	v_fmac_f32_e32 v42, v19, v74
	v_fmac_f32_e32 v43, v19, v75
	v_fmac_f32_e32 v44, v19, v76
	v_fmac_f32_e32 v45, v19, v77
	v_fmac_f32_e32 v46, v19, v78
	v_fmac_f32_e32 v47, v19, v79
	v_fmac_f32_e32 v48, v19, v80
	v_fmac_f32_e32 v49, v19, v81
	v_fmac_f32_e32 v50, v19, v82
	v_fmac_f32_e32 v51, v19, v83
	v_fmac_f32_e32 v52, v19, v84
	v_fmac_f32_e32 v53, v19, v85
	v_fmac_f32_e32 v54, v19, v86
	v_fmac_f32_e32 v55, v19, v87
	v_fmac_f32_e32 v56, v19, v88
	v_fmac_f32_e32 v57, v19, v89
	ds_read_b128 v[74:77], v2 offset:35008
	ds_read_b128 v[78:81], v2 offset:35024
	ds_read_b128 v[82:85], v2 offset:35040
	ds_read_b128 v[86:89], v2 offset:35056
	s_waitcnt lgkmcnt(4)
	v_fmac_f32_e32 v42, v20, v58
	v_fmac_f32_e32 v43, v20, v59
	v_fmac_f32_e32 v44, v20, v60
	v_fmac_f32_e32 v45, v20, v61
	v_fmac_f32_e32 v46, v20, v62
	v_fmac_f32_e32 v47, v20, v63
	v_fmac_f32_e32 v48, v20, v64
	v_fmac_f32_e32 v49, v20, v65
	v_fmac_f32_e32 v50, v20, v66
	v_fmac_f32_e32 v51, v20, v67
	v_fmac_f32_e32 v52, v20, v68
	v_fmac_f32_e32 v53, v20, v69
	v_fmac_f32_e32 v54, v20, v70
	v_fmac_f32_e32 v55, v20, v71
	v_fmac_f32_e32 v56, v20, v72
	v_fmac_f32_e32 v57, v20, v73
	ds_read_b128 v[58:61], v2 offset:52224
	ds_read_b128 v[62:65], v2 offset:52240
	ds_read_b128 v[66:69], v2 offset:52256
	ds_read_b128 v[70:73], v2 offset:52272
	s_waitcnt lgkmcnt(4)
	v_fmac_f32_e32 v42, v21, v74
	v_fmac_f32_e32 v43, v21, v75
	v_fmac_f32_e32 v44, v21, v76
	v_fmac_f32_e32 v45, v21, v77
	v_fmac_f32_e32 v46, v21, v78
	v_fmac_f32_e32 v47, v21, v79
	v_fmac_f32_e32 v48, v21, v80
	v_fmac_f32_e32 v49, v21, v81
	v_fmac_f32_e32 v50, v21, v82
	v_fmac_f32_e32 v51, v21, v83
	v_fmac_f32_e32 v52, v21, v84
	v_fmac_f32_e32 v53, v21, v85
	v_fmac_f32_e32 v54, v21, v86
	v_fmac_f32_e32 v55, v21, v87
	v_fmac_f32_e32 v56, v21, v88
	v_fmac_f32_e32 v57, v21, v89
	ds_read_b128 v[74:77], v2 offset:52288
	ds_read_b128 v[78:81], v2 offset:52304
	ds_read_b128 v[82:85], v2 offset:52320
	ds_read_b128 v[86:89], v2 offset:52336
	s_waitcnt lgkmcnt(4)
; DEVINL void phase7(const Params& p) {
;     ...
; #pragma unroll
;       for (int q = 0; q < 4; ++q) {
;         const float4* wr = (const float4*)(p.w_router + (long)(c + q) * 16);
; #pragma unroll
;         for (int e4 = 0; e4 < 4; ++e4) {
;           float4 w = wr[e4];
;           lg[e4 * 4 + 0] += hh[q] * w.x; lg[e4 * 4 + 1] += hh[q] * w.y;
;           lg[e4 * 4 + 2] += hh[q] * w.z; lg[e4 * 4 + 3] += hh[q] * w.w;
;         }
;       }
	v_fmac_f32_e32 v42, v22, v58
	v_fmac_f32_e32 v43, v22, v59
	v_fmac_f32_e32 v44, v22, v60
	v_fmac_f32_e32 v45, v22, v61
	v_fmac_f32_e32 v46, v22, v62
	v_fmac_f32_e32 v47, v22, v63
	v_fmac_f32_e32 v48, v22, v64
	v_fmac_f32_e32 v49, v22, v65
	v_fmac_f32_e32 v50, v22, v66
	v_fmac_f32_e32 v51, v22, v67
	v_fmac_f32_e32 v52, v22, v68
	v_fmac_f32_e32 v53, v22, v69
	v_fmac_f32_e32 v54, v22, v70
	v_fmac_f32_e32 v55, v22, v71
	v_fmac_f32_e32 v56, v22, v72
	v_fmac_f32_e32 v57, v22, v73
	ds_read_b128 v[58:61], v2 offset:52352
	ds_read_b128 v[62:65], v2 offset:52368
	ds_read_b128 v[66:69], v2 offset:52384
	ds_read_b128 v[70:73], v2 offset:52400
	s_waitcnt lgkmcnt(4)
	v_fmac_f32_e32 v42, v23, v74
	v_fmac_f32_e32 v43, v23, v75
	v_fmac_f32_e32 v44, v23, v76
	v_fmac_f32_e32 v45, v23, v77
	v_fmac_f32_e32 v46, v23, v78
	v_fmac_f32_e32 v47, v23, v79
	v_fmac_f32_e32 v48, v23, v80
	v_fmac_f32_e32 v49, v23, v81
	v_fmac_f32_e32 v50, v23, v82
	v_fmac_f32_e32 v51, v23, v83
	v_fmac_f32_e32 v52, v23, v84
	v_fmac_f32_e32 v53, v23, v85
	v_fmac_f32_e32 v54, v23, v86
	v_fmac_f32_e32 v55, v23, v87
	v_fmac_f32_e32 v56, v23, v88
	v_fmac_f32_e32 v57, v23, v89
	ds_read_b128 v[74:77], v2 offset:52416
	ds_read_b128 v[78:81], v2 offset:52432
	ds_read_b128 v[82:85], v2 offset:52448
	ds_read_b128 v[86:89], v2 offset:52464
	s_waitcnt lgkmcnt(4)
	v_fmac_f32_e32 v42, v24, v58
	v_fmac_f32_e32 v43, v24, v59
	v_fmac_f32_e32 v44, v24, v60
	v_fmac_f32_e32 v45, v24, v61
	v_fmac_f32_e32 v46, v24, v62
	v_fmac_f32_e32 v47, v24, v63
	v_fmac_f32_e32 v48, v24, v64
	v_fmac_f32_e32 v49, v24, v65
	v_fmac_f32_e32 v50, v24, v66
	v_fmac_f32_e32 v51, v24, v67
	v_fmac_f32_e32 v52, v24, v68
	v_fmac_f32_e32 v53, v24, v69
	v_fmac_f32_e32 v54, v24, v70
	v_fmac_f32_e32 v55, v24, v71
	v_fmac_f32_e32 v56, v24, v72
	v_fmac_f32_e32 v57, v24, v73
	ds_read_b128 v[58:61], v3 offset:0
	ds_read_b128 v[62:65], v3 offset:16
	ds_read_b128 v[66:69], v3 offset:32
	ds_read_b128 v[70:73], v3 offset:48
	s_waitcnt lgkmcnt(4)
	v_fmac_f32_e32 v42, v25, v74
	v_fmac_f32_e32 v43, v25, v75
	v_fmac_f32_e32 v44, v25, v76
	v_fmac_f32_e32 v45, v25, v77
	v_fmac_f32_e32 v46, v25, v78
	v_fmac_f32_e32 v47, v25, v79
	v_fmac_f32_e32 v48, v25, v80
	v_fmac_f32_e32 v49, v25, v81
	v_fmac_f32_e32 v50, v25, v82
	v_fmac_f32_e32 v51, v25, v83
	v_fmac_f32_e32 v52, v25, v84
	v_fmac_f32_e32 v53, v25, v85
	v_fmac_f32_e32 v54, v25, v86
	v_fmac_f32_e32 v55, v25, v87
	v_fmac_f32_e32 v56, v25, v88
	v_fmac_f32_e32 v57, v25, v89
	ds_read_b128 v[74:77], v3 offset:64
	ds_read_b128 v[78:81], v3 offset:80
	ds_read_b128 v[82:85], v3 offset:96
	ds_read_b128 v[86:89], v3 offset:112
	s_waitcnt lgkmcnt(4)
	v_fmac_f32_e32 v42, v26, v58
	v_fmac_f32_e32 v43, v26, v59
	v_fmac_f32_e32 v44, v26, v60
	v_fmac_f32_e32 v45, v26, v61
	v_fmac_f32_e32 v46, v26, v62
	v_fmac_f32_e32 v47, v26, v63
	v_fmac_f32_e32 v48, v26, v64
	v_fmac_f32_e32 v49, v26, v65
	v_fmac_f32_e32 v50, v26, v66
	v_fmac_f32_e32 v51, v26, v67
	v_fmac_f32_e32 v52, v26, v68
	v_fmac_f32_e32 v53, v26, v69
	v_fmac_f32_e32 v54, v26, v70
	v_fmac_f32_e32 v55, v26, v71
	v_fmac_f32_e32 v56, v26, v72
	v_fmac_f32_e32 v57, v26, v73
	ds_read_b128 v[58:61], v3 offset:128
	ds_read_b128 v[62:65], v3 offset:144
	ds_read_b128 v[66:69], v3 offset:160
	ds_read_b128 v[70:73], v3 offset:176
	s_waitcnt lgkmcnt(4)
	v_fmac_f32_e32 v42, v27, v74
	v_fmac_f32_e32 v43, v27, v75
	v_fmac_f32_e32 v44, v27, v76
	v_fmac_f32_e32 v45, v27, v77
	v_fmac_f32_e32 v46, v27, v78
	v_fmac_f32_e32 v47, v27, v79
	v_fmac_f32_e32 v48, v27, v80
	v_fmac_f32_e32 v49, v27, v81
	v_fmac_f32_e32 v50, v27, v82
	v_fmac_f32_e32 v51, v27, v83
	v_fmac_f32_e32 v52, v27, v84
	v_fmac_f32_e32 v53, v27, v85
	v_fmac_f32_e32 v54, v27, v86
	v_fmac_f32_e32 v55, v27, v87
	v_fmac_f32_e32 v56, v27, v88
	v_fmac_f32_e32 v57, v27, v89
	ds_read_b128 v[74:77], v3 offset:192
	ds_read_b128 v[78:81], v3 offset:208
	ds_read_b128 v[82:85], v3 offset:224
	ds_read_b128 v[86:89], v3 offset:240
	s_waitcnt lgkmcnt(4)
	v_fmac_f32_e32 v42, v28, v58
	v_fmac_f32_e32 v43, v28, v59
	v_fmac_f32_e32 v44, v28, v60
	v_fmac_f32_e32 v45, v28, v61
	v_fmac_f32_e32 v46, v28, v62
	v_fmac_f32_e32 v47, v28, v63
	v_fmac_f32_e32 v48, v28, v64
	v_fmac_f32_e32 v49, v28, v65
	v_fmac_f32_e32 v50, v28, v66
	v_fmac_f32_e32 v51, v28, v67
	v_fmac_f32_e32 v52, v28, v68
	v_fmac_f32_e32 v53, v28, v69
	v_fmac_f32_e32 v54, v28, v70
	v_fmac_f32_e32 v55, v28, v71
	v_fmac_f32_e32 v56, v28, v72
	v_fmac_f32_e32 v57, v28, v73
	ds_read_b128 v[58:61], v3 offset:17408
	ds_read_b128 v[62:65], v3 offset:17424
	ds_read_b128 v[66:69], v3 offset:17440
	ds_read_b128 v[70:73], v3 offset:17456
	s_waitcnt lgkmcnt(4)
	v_fmac_f32_e32 v42, v29, v74
	v_fmac_f32_e32 v43, v29, v75
	v_fmac_f32_e32 v44, v29, v76
	v_fmac_f32_e32 v45, v29, v77
	v_fmac_f32_e32 v46, v29, v78
	v_fmac_f32_e32 v47, v29, v79
	v_fmac_f32_e32 v48, v29, v80
	v_fmac_f32_e32 v49, v29, v81
	v_fmac_f32_e32 v50, v29, v82
	v_fmac_f32_e32 v51, v29, v83
	v_fmac_f32_e32 v52, v29, v84
	v_fmac_f32_e32 v53, v29, v85
	v_fmac_f32_e32 v54, v29, v86
	v_fmac_f32_e32 v55, v29, v87
	v_fmac_f32_e32 v56, v29, v88
	v_fmac_f32_e32 v57, v29, v89
	ds_read_b128 v[74:77], v3 offset:17472
	ds_read_b128 v[78:81], v3 offset:17488
	ds_read_b128 v[82:85], v3 offset:17504
	ds_read_b128 v[86:89], v3 offset:17520
	s_waitcnt lgkmcnt(4)
	v_fmac_f32_e32 v42, v30, v58
	v_fmac_f32_e32 v43, v30, v59
	v_fmac_f32_e32 v44, v30, v60
	v_fmac_f32_e32 v45, v30, v61
	v_fmac_f32_e32 v46, v30, v62
	v_fmac_f32_e32 v47, v30, v63
	v_fmac_f32_e32 v48, v30, v64
	v_fmac_f32_e32 v49, v30, v65
	v_fmac_f32_e32 v50, v30, v66
	v_fmac_f32_e32 v51, v30, v67
	v_fmac_f32_e32 v52, v30, v68
	v_fmac_f32_e32 v53, v30, v69
	v_fmac_f32_e32 v54, v30, v70
	v_fmac_f32_e32 v55, v30, v71
	v_fmac_f32_e32 v56, v30, v72
	v_fmac_f32_e32 v57, v30, v73
	ds_read_b128 v[58:61], v3 offset:17536
	ds_read_b128 v[62:65], v3 offset:17552
	ds_read_b128 v[66:69], v3 offset:17568
	ds_read_b128 v[70:73], v3 offset:17584
	s_waitcnt lgkmcnt(4)
; DEVINL void phase7(const Params& p) {
;     ...
; #pragma unroll
;       for (int q = 0; q < 4; ++q) {
;         const float4* wr = (const float4*)(p.w_router + (long)(c + q) * 16);
; #pragma unroll
;         for (int e4 = 0; e4 < 4; ++e4) {
;           float4 w = wr[e4];
;           lg[e4 * 4 + 0] += hh[q] * w.x; lg[e4 * 4 + 1] += hh[q] * w.y;
;           lg[e4 * 4 + 2] += hh[q] * w.z; lg[e4 * 4 + 3] += hh[q] * w.w;
;         }
;       }
	v_fmac_f32_e32 v42, v31, v74
	v_fmac_f32_e32 v43, v31, v75
	v_fmac_f32_e32 v44, v31, v76
	v_fmac_f32_e32 v45, v31, v77
	v_fmac_f32_e32 v46, v31, v78
	v_fmac_f32_e32 v47, v31, v79
	v_fmac_f32_e32 v48, v31, v80
	v_fmac_f32_e32 v49, v31, v81
	v_fmac_f32_e32 v50, v31, v82
	v_fmac_f32_e32 v51, v31, v83
	v_fmac_f32_e32 v52, v31, v84
	v_fmac_f32_e32 v53, v31, v85
	v_fmac_f32_e32 v54, v31, v86
	v_fmac_f32_e32 v55, v31, v87
	v_fmac_f32_e32 v56, v31, v88
	v_fmac_f32_e32 v57, v31, v89
	ds_read_b128 v[74:77], v3 offset:17600
	ds_read_b128 v[78:81], v3 offset:17616
	ds_read_b128 v[82:85], v3 offset:17632
	ds_read_b128 v[86:89], v3 offset:17648
	s_waitcnt lgkmcnt(4)
	v_fmac_f32_e32 v42, v32, v58
	v_fmac_f32_e32 v43, v32, v59
	v_fmac_f32_e32 v44, v32, v60
	v_fmac_f32_e32 v45, v32, v61
	v_fmac_f32_e32 v46, v32, v62
	v_fmac_f32_e32 v47, v32, v63
	v_fmac_f32_e32 v48, v32, v64
	v_fmac_f32_e32 v49, v32, v65
	v_fmac_f32_e32 v50, v32, v66
	v_fmac_f32_e32 v51, v32, v67
	v_fmac_f32_e32 v52, v32, v68
	v_fmac_f32_e32 v53, v32, v69
	v_fmac_f32_e32 v54, v32, v70
	v_fmac_f32_e32 v55, v32, v71
	v_fmac_f32_e32 v56, v32, v72
	v_fmac_f32_e32 v57, v32, v73
	ds_read_b128 v[58:61], v3 offset:34816
	ds_read_b128 v[62:65], v3 offset:34832
	ds_read_b128 v[66:69], v3 offset:34848
	ds_read_b128 v[70:73], v3 offset:34864
	s_waitcnt lgkmcnt(4)
	v_fmac_f32_e32 v42, v33, v74
	v_fmac_f32_e32 v43, v33, v75
	v_fmac_f32_e32 v44, v33, v76
	v_fmac_f32_e32 v45, v33, v77
	v_fmac_f32_e32 v46, v33, v78
	v_fmac_f32_e32 v47, v33, v79
	v_fmac_f32_e32 v48, v33, v80
	v_fmac_f32_e32 v49, v33, v81
	v_fmac_f32_e32 v50, v33, v82
	v_fmac_f32_e32 v51, v33, v83
	v_fmac_f32_e32 v52, v33, v84
	v_fmac_f32_e32 v53, v33, v85
	v_fmac_f32_e32 v54, v33, v86
	v_fmac_f32_e32 v55, v33, v87
	v_fmac_f32_e32 v56, v33, v88
	v_fmac_f32_e32 v57, v33, v89
	ds_read_b128 v[74:77], v3 offset:34880
	ds_read_b128 v[78:81], v3 offset:34896
	ds_read_b128 v[82:85], v3 offset:34912
	ds_read_b128 v[86:89], v3 offset:34928
	s_waitcnt lgkmcnt(4)
	v_fmac_f32_e32 v42, v34, v58
	v_fmac_f32_e32 v43, v34, v59
	v_fmac_f32_e32 v44, v34, v60
	v_fmac_f32_e32 v45, v34, v61
	v_fmac_f32_e32 v46, v34, v62
	v_fmac_f32_e32 v47, v34, v63
	v_fmac_f32_e32 v48, v34, v64
	v_fmac_f32_e32 v49, v34, v65
	v_fmac_f32_e32 v50, v34, v66
	v_fmac_f32_e32 v51, v34, v67
	v_fmac_f32_e32 v52, v34, v68
	v_fmac_f32_e32 v53, v34, v69
	v_fmac_f32_e32 v54, v34, v70
	v_fmac_f32_e32 v55, v34, v71
	v_fmac_f32_e32 v56, v34, v72
	v_fmac_f32_e32 v57, v34, v73
	ds_read_b128 v[58:61], v3 offset:34944
	ds_read_b128 v[62:65], v3 offset:34960
	ds_read_b128 v[66:69], v3 offset:34976
	ds_read_b128 v[70:73], v3 offset:34992
	s_waitcnt lgkmcnt(4)
	v_fmac_f32_e32 v42, v35, v74
	v_fmac_f32_e32 v43, v35, v75
	v_fmac_f32_e32 v44, v35, v76
	v_fmac_f32_e32 v45, v35, v77
	v_fmac_f32_e32 v46, v35, v78
	v_fmac_f32_e32 v47, v35, v79
	v_fmac_f32_e32 v48, v35, v80
	v_fmac_f32_e32 v49, v35, v81
	v_fmac_f32_e32 v50, v35, v82
	v_fmac_f32_e32 v51, v35, v83
	v_fmac_f32_e32 v52, v35, v84
	v_fmac_f32_e32 v53, v35, v85
	v_fmac_f32_e32 v54, v35, v86
	v_fmac_f32_e32 v55, v35, v87
	v_fmac_f32_e32 v56, v35, v88
	v_fmac_f32_e32 v57, v35, v89
	ds_read_b128 v[74:77], v3 offset:35008
	ds_read_b128 v[78:81], v3 offset:35024
	ds_read_b128 v[82:85], v3 offset:35040
	ds_read_b128 v[86:89], v3 offset:35056
	s_waitcnt lgkmcnt(4)
	v_fmac_f32_e32 v42, v36, v58
	v_fmac_f32_e32 v43, v36, v59
	v_fmac_f32_e32 v44, v36, v60
	v_fmac_f32_e32 v45, v36, v61
	v_fmac_f32_e32 v46, v36, v62
	v_fmac_f32_e32 v47, v36, v63
	v_fmac_f32_e32 v48, v36, v64
	v_fmac_f32_e32 v49, v36, v65
	v_fmac_f32_e32 v50, v36, v66
	v_fmac_f32_e32 v51, v36, v67
	v_fmac_f32_e32 v52, v36, v68
	v_fmac_f32_e32 v53, v36, v69
	v_fmac_f32_e32 v54, v36, v70
	v_fmac_f32_e32 v55, v36, v71
	v_fmac_f32_e32 v56, v36, v72
	v_fmac_f32_e32 v57, v36, v73
	ds_read_b128 v[58:61], v3 offset:52224
	ds_read_b128 v[62:65], v3 offset:52240
	ds_read_b128 v[66:69], v3 offset:52256
	ds_read_b128 v[70:73], v3 offset:52272
	s_waitcnt lgkmcnt(4)
	v_fmac_f32_e32 v42, v37, v74
	v_fmac_f32_e32 v43, v37, v75
	v_fmac_f32_e32 v44, v37, v76
	v_fmac_f32_e32 v45, v37, v77
	v_fmac_f32_e32 v46, v37, v78
	v_fmac_f32_e32 v47, v37, v79
	v_fmac_f32_e32 v48, v37, v80
	v_fmac_f32_e32 v49, v37, v81
	v_fmac_f32_e32 v50, v37, v82
	v_fmac_f32_e32 v51, v37, v83
	v_fmac_f32_e32 v52, v37, v84
	v_fmac_f32_e32 v53, v37, v85
	v_fmac_f32_e32 v54, v37, v86
	v_fmac_f32_e32 v55, v37, v87
	v_fmac_f32_e32 v56, v37, v88
	v_fmac_f32_e32 v57, v37, v89
	ds_read_b128 v[74:77], v3 offset:52288
	ds_read_b128 v[78:81], v3 offset:52304
	ds_read_b128 v[82:85], v3 offset:52320
	ds_read_b128 v[86:89], v3 offset:52336
	s_waitcnt lgkmcnt(4)
	v_fmac_f32_e32 v42, v38, v58
	v_fmac_f32_e32 v43, v38, v59
	v_fmac_f32_e32 v44, v38, v60
	v_fmac_f32_e32 v45, v38, v61
	v_fmac_f32_e32 v46, v38, v62
	v_fmac_f32_e32 v47, v38, v63
	v_fmac_f32_e32 v48, v38, v64
	v_fmac_f32_e32 v49, v38, v65
	v_fmac_f32_e32 v50, v38, v66
	v_fmac_f32_e32 v51, v38, v67
	v_fmac_f32_e32 v52, v38, v68
	v_fmac_f32_e32 v53, v38, v69
	v_fmac_f32_e32 v54, v38, v70
	v_fmac_f32_e32 v55, v38, v71
	v_fmac_f32_e32 v56, v38, v72
	v_fmac_f32_e32 v57, v38, v73
	ds_read_b128 v[58:61], v3 offset:52352
	ds_read_b128 v[62:65], v3 offset:52368
	ds_read_b128 v[66:69], v3 offset:52384
	ds_read_b128 v[70:73], v3 offset:52400
	s_waitcnt lgkmcnt(4)
	v_fmac_f32_e32 v42, v39, v74
	v_fmac_f32_e32 v43, v39, v75
	v_fmac_f32_e32 v44, v39, v76
	v_fmac_f32_e32 v45, v39, v77
	v_fmac_f32_e32 v46, v39, v78
	v_fmac_f32_e32 v47, v39, v79
	v_fmac_f32_e32 v48, v39, v80
	v_fmac_f32_e32 v49, v39, v81
	v_fmac_f32_e32 v50, v39, v82
	v_fmac_f32_e32 v51, v39, v83
	v_fmac_f32_e32 v52, v39, v84
	v_fmac_f32_e32 v53, v39, v85
	v_fmac_f32_e32 v54, v39, v86
	v_fmac_f32_e32 v55, v39, v87
	v_fmac_f32_e32 v56, v39, v88
	v_fmac_f32_e32 v57, v39, v89
	ds_read_b128 v[74:77], v3 offset:52416
	ds_read_b128 v[78:81], v3 offset:52432
	ds_read_b128 v[82:85], v3 offset:52448
	ds_read_b128 v[86:89], v3 offset:52464
	s_waitcnt lgkmcnt(4)
; DEVINL void phase7(const Params& p) {
;     ...
; #pragma unroll
;       for (int q = 0; q < 4; ++q) {
;         const float4* wr = (const float4*)(p.w_router + (long)(c + q) * 16);
; #pragma unroll
;         for (int e4 = 0; e4 < 4; ++e4) {
;           float4 w = wr[e4];
;           lg[e4 * 4 + 0] += hh[q] * w.x; lg[e4 * 4 + 1] += hh[q] * w.y;
;           lg[e4 * 4 + 2] += hh[q] * w.z; lg[e4 * 4 + 3] += hh[q] * w.w;
;         }
;       }
;     }
;     float mx = -1e30f;
; #pragma unroll
;     for (int e = 0; e < 16; ++e) { lg[e] = allred64(lg[e]); mx = fmaxf(mx, lg[e]); }
;     float den = 0.f;
; #pragma unroll
;     for (int e = 0; e < 16; ++e) { lg[e] = __expf(lg[e] - mx); den += lg[e]; }
;     const float inv = 1.f / den;
;     float mine = 0.f;
; #pragma unroll
;     for (int e = 0; e < 16; ++e) if (lane == e) mine = lg[e] * inv;
;     if (lane < 16) {
;       const int b = row >> 12, s = row & 4095;
;       ((float*)(ws + O_AFF))[((long)(b * 16 + lane)) * 4096 + s] = mine;
;       ((int*)(ws + O_INV))[row * 16 + lane] = -1;
;     }
	v_fmac_f32_e32 v42, v40, v58
	v_fmac_f32_e32 v43, v40, v59
	v_fmac_f32_e32 v44, v40, v60
	v_fmac_f32_e32 v45, v40, v61
	v_fmac_f32_e32 v46, v40, v62
	v_fmac_f32_e32 v47, v40, v63
	v_fmac_f32_e32 v48, v40, v64
	v_fmac_f32_e32 v49, v40, v65
	v_fmac_f32_e32 v50, v40, v66
	v_fmac_f32_e32 v51, v40, v67
	v_fmac_f32_e32 v52, v40, v68
	v_fmac_f32_e32 v53, v40, v69
	v_fmac_f32_e32 v54, v40, v70
	v_fmac_f32_e32 v55, v40, v71
	v_fmac_f32_e32 v56, v40, v72
	v_fmac_f32_e32 v57, v40, v73
	s_waitcnt lgkmcnt(0)
	v_fmac_f32_e32 v42, v41, v74
	v_fmac_f32_e32 v43, v41, v75
	v_fmac_f32_e32 v44, v41, v76
	v_fmac_f32_e32 v45, v41, v77
	v_fmac_f32_e32 v46, v41, v78
	v_fmac_f32_e32 v47, v41, v79
	v_fmac_f32_e32 v48, v41, v80
	v_fmac_f32_e32 v49, v41, v81
	v_fmac_f32_e32 v50, v41, v82
	v_fmac_f32_e32 v51, v41, v83
	v_fmac_f32_e32 v52, v41, v84
	v_fmac_f32_e32 v53, v41, v85
	v_fmac_f32_e32 v54, v41, v86
	v_fmac_f32_e32 v55, v41, v87
	v_fmac_f32_e32 v56, v41, v88
	v_fmac_f32_e32 v57, v41, v89
	v_add_f32_dpp v8, v42, v42 quad_perm:[1,0,3,2] row_mask:0xf bank_mask:0xf bound_ctrl:1
	v_add_f32_dpp v9, v43, v43 quad_perm:[1,0,3,2] row_mask:0xf bank_mask:0xf bound_ctrl:1
	v_cndmask_b32_e64 v170, v8, v9, s[14:15]
	v_add_f32_dpp v8, v44, v44 quad_perm:[1,0,3,2] row_mask:0xf bank_mask:0xf bound_ctrl:1
	v_add_f32_dpp v9, v45, v45 quad_perm:[1,0,3,2] row_mask:0xf bank_mask:0xf bound_ctrl:1
	v_cndmask_b32_e64 v171, v8, v9, s[14:15]
	v_add_f32_dpp v8, v46, v46 quad_perm:[1,0,3,2] row_mask:0xf bank_mask:0xf bound_ctrl:1
	v_add_f32_dpp v9, v47, v47 quad_perm:[1,0,3,2] row_mask:0xf bank_mask:0xf bound_ctrl:1
	v_cndmask_b32_e64 v172, v8, v9, s[14:15]
	v_add_f32_dpp v8, v48, v48 quad_perm:[1,0,3,2] row_mask:0xf bank_mask:0xf bound_ctrl:1
	v_add_f32_dpp v9, v49, v49 quad_perm:[1,0,3,2] row_mask:0xf bank_mask:0xf bound_ctrl:1
	v_cndmask_b32_e64 v173, v8, v9, s[14:15]
	v_add_f32_dpp v8, v50, v50 quad_perm:[1,0,3,2] row_mask:0xf bank_mask:0xf bound_ctrl:1
	v_add_f32_dpp v9, v51, v51 quad_perm:[1,0,3,2] row_mask:0xf bank_mask:0xf bound_ctrl:1
	v_cndmask_b32_e64 v174, v8, v9, s[14:15]
	v_add_f32_dpp v8, v52, v52 quad_perm:[1,0,3,2] row_mask:0xf bank_mask:0xf bound_ctrl:1
	v_add_f32_dpp v9, v53, v53 quad_perm:[1,0,3,2] row_mask:0xf bank_mask:0xf bound_ctrl:1
	v_cndmask_b32_e64 v175, v8, v9, s[14:15]
	v_add_f32_dpp v8, v54, v54 quad_perm:[1,0,3,2] row_mask:0xf bank_mask:0xf bound_ctrl:1
	v_add_f32_dpp v9, v55, v55 quad_perm:[1,0,3,2] row_mask:0xf bank_mask:0xf bound_ctrl:1
	v_cndmask_b32_e64 v176, v8, v9, s[14:15]
	v_add_f32_dpp v8, v56, v56 quad_perm:[1,0,3,2] row_mask:0xf bank_mask:0xf bound_ctrl:1
	v_add_f32_dpp v9, v57, v57 quad_perm:[1,0,3,2] row_mask:0xf bank_mask:0xf bound_ctrl:1
	v_cndmask_b32_e64 v177, v8, v9, s[14:15]
	v_add_f32_dpp v8, v170, v170 quad_perm:[2,3,0,1] row_mask:0xf bank_mask:0xf bound_ctrl:1
	v_add_f32_dpp v9, v171, v171 quad_perm:[2,3,0,1] row_mask:0xf bank_mask:0xf bound_ctrl:1
	v_cndmask_b32_e64 v178, v8, v9, s[16:17]
	v_add_f32_dpp v8, v172, v172 quad_perm:[2,3,0,1] row_mask:0xf bank_mask:0xf bound_ctrl:1
	v_add_f32_dpp v9, v173, v173 quad_perm:[2,3,0,1] row_mask:0xf bank_mask:0xf bound_ctrl:1
	v_cndmask_b32_e64 v179, v8, v9, s[16:17]
	v_add_f32_dpp v8, v174, v174 quad_perm:[2,3,0,1] row_mask:0xf bank_mask:0xf bound_ctrl:1
	v_add_f32_dpp v9, v175, v175 quad_perm:[2,3,0,1] row_mask:0xf bank_mask:0xf bound_ctrl:1
	v_cndmask_b32_e64 v180, v8, v9, s[16:17]
	v_add_f32_dpp v8, v176, v176 quad_perm:[2,3,0,1] row_mask:0xf bank_mask:0xf bound_ctrl:1
	v_add_f32_dpp v9, v177, v177 quad_perm:[2,3,0,1] row_mask:0xf bank_mask:0xf bound_ctrl:1
	v_cndmask_b32_e64 v181, v8, v9, s[16:17]
	s_nop 1
	v_add_f32_dpp v182, v178, v178 row_ror:12 row_mask:0xf bank_mask:0x5
	v_add_f32_dpp v182, v179, v179 row_ror:4 row_mask:0xf bank_mask:0xa
	v_add_f32_dpp v183, v180, v180 row_ror:12 row_mask:0xf bank_mask:0x5
	v_add_f32_dpp v183, v181, v181 row_ror:4 row_mask:0xf bank_mask:0xa
	s_nop 1
	v_add_f32_dpp v184, v182, v182 row_ror:8 row_mask:0xf bank_mask:0x3
	v_add_f32_dpp v184, v183, v183 row_ror:8 row_mask:0xf bank_mask:0xc
	ds_bpermute_b32 v8, v6, v184
	s_waitcnt lgkmcnt(0)
	v_add_f32_e32 v184, v184, v8
	ds_bpermute_b32 v8, v7, v184
	s_waitcnt lgkmcnt(0)
	v_add_f32_e32 v184, v184, v8
	v_mov_b32_e32 v8, v184
	s_nop 1
	v_max_f32_dpp v8, v8, v8 quad_perm:[1,0,3,2] row_mask:0xf bank_mask:0xf bound_ctrl:1
	s_nop 1
	v_max_f32_dpp v8, v8, v8 quad_perm:[2,3,0,1] row_mask:0xf bank_mask:0xf bound_ctrl:1
	s_nop 1
	v_max_f32_dpp v8, v8, v8 row_half_mirror row_mask:0xf bank_mask:0xf bound_ctrl:1
	s_nop 1
	v_max_f32_dpp v8, v8, v8 row_mirror row_mask:0xf bank_mask:0xf bound_ctrl:1
	v_sub_f32_e32 v9, v184, v8
	v_mul_f32_e32 v9, 0x3fb8aa3b, v9
	v_exp_f32_e32 v9, v9
	s_nop 0
	v_mov_b32_e32 v8, v9
	s_nop 1
	v_add_f32_dpp v8, v8, v8 quad_perm:[1,0,3,2] row_mask:0xf bank_mask:0xf bound_ctrl:1
	s_nop 1
	v_add_f32_dpp v8, v8, v8 quad_perm:[2,3,0,1] row_mask:0xf bank_mask:0xf bound_ctrl:1
	s_nop 1
	v_add_f32_dpp v8, v8, v8 row_half_mirror row_mask:0xf bank_mask:0xf bound_ctrl:1
	s_nop 1
	v_add_f32_dpp v8, v8, v8 row_mirror row_mask:0xf bank_mask:0xf bound_ctrl:1
	v_div_scale_f32 v170, s[24:25], v8, v8, 1.0
	v_rcp_f32_e32 v171, v170
	s_nop 0
	v_fma_f32 v172, -v170, v171, 1.0
	v_fmac_f32_e32 v171, v172, v171
	v_div_scale_f32 v173, vcc, 1.0, v8, 1.0
	v_mul_f32_e32 v174, v173, v171
	v_fma_f32 v175, -v170, v174, v173
	v_fmac_f32_e32 v174, v175, v171
	v_fma_f32 v170, -v170, v174, v173
	v_div_fmas_f32 v170, v170, v171, v174
	v_div_fixup_f32 v8, v170, v8, 1.0
	v_mul_f32_e32 v9, v9, v8
	s_lshr_b32 s0, s4, 12
	s_lshl_b32 s0, s0, 18
	s_and_b32 s1, s4, 0xfff
	s_lshl_b32 s1, s1, 2
	s_add_u32 s0, s0, s1
	s_add_u32 s10, s92, s0
	s_addc_u32 s11, s93, 0
	s_add_u32 s10, s10, 0x1f600000
	s_addc_u32 s11, s11, 0
	s_lshl_b32 s0, s4, 6
	s_add_u32 s12, s92, s0
	s_addc_u32 s13, s93, 0
	s_add_u32 s12, s12, 0x21700000
	s_addc_u32 s13, s13, 0
	s_mov_b64 exec, 0xffff
	global_store_dword v5, v9, s[10:11]
	global_store_dword v4, v187, s[12:13]
	s_mov_b64 exec, -1
	s_add_u32 s4, s4, s5
	s_cmp_lt_u32 s4, 0x2000
	s_cbranch_scc1 .Lp7_row
; DEVINL unsigned xb_ld(unsigned* p_) { return __hip_atomic_load(p_, __ATOMIC_RELAXED, __HIP_MEMORY_SCOPE_AGENT); }
; DEVINL void xcd_barrier_complete(unsigned* bar, unsigned x, unsigned& nloc, unsigned& nx) {
;   const unsigned G = gridDim.x * gridDim.y * gridDim.z;
;   unsigned sum, cnt, mine, sp = 0u;
;   for (;;) {
;     sum = 0u; cnt = 0u; mine = 0u;
; #pragma unroll
;     for (unsigned j = 0; j < 16; ++j) { const unsigned c = xb_ld(&bar[XB_XCNT(j)]); sum += c; cnt += (c > 0u) ? 1u : 0u; mine = (j == x) ? c : mine; }
; DEVINL void xcd_barrier(const XcdBarrier& b) {
;   asm volatile("s_waitcnt vmcnt(0)" ::: "memory");
;   __syncthreads();
;   if (threadIdx.x == 0) {
;     unsigned* bar = b.bar;
;     __builtin_amdgcn_s_waitcnt(0);
;     unsigned nloc = b.st[0], nx = b.st[1];
;     if (nloc == 0u) { xcd_barrier_complete(bar, b.x, nloc, nx); b.st[0] = nloc; b.st[1] = nx; }
.Lp7_end:
	s_mov_b64 exec, -1
	s_waitcnt vmcnt(0)
	s_barrier
	s_mov_b64 s[0:1], exec
	v_readlane_b32 s4, v254, 0
	v_readlane_b32 s5, v254, 1
	s_and_b64 s[4:5], s[0:1], s[4:5]
	s_mov_b64 exec, s[4:5]
	s_cbranch_execz .LBB0_794
	v_mov_b32_e32 v0, 0
	s_waitcnt vmcnt(0) expcnt(0) lgkmcnt(0)
	ds_read_b32 v2, v0
	ds_read_b32 v1, v0 offset:4
	s_waitcnt lgkmcnt(1)
	v_cmp_ne_u32_e32 vcc, 0, v2
	s_cbranch_vccnz .LBB0_758
	s_add_u32 s4, s92, 0x217c0200
	s_addc_u32 s5, s93, 0
	s_add_u32 s6, s92, 0x217c0400
	s_addc_u32 s7, s93, 0
	s_add_u32 s8, s92, 0x217c0500
	s_addc_u32 s9, s93, 0
	s_add_u32 s10, s92, 0x217c0600
	s_addc_u32 s11, s93, 0
	s_add_u32 s12, s92, 0x217c0700
	s_addc_u32 s13, s93, 0
	s_add_u32 s14, s92, 0x217c0800
	s_addc_u32 s15, s93, 0
	s_add_u32 s16, s92, 0x217c0900
	s_addc_u32 s17, s93, 0
	s_add_u32 s18, s92, 0x217c0a00
	s_addc_u32 s19, s93, 0
	s_add_u32 s20, s92, 0x217c0b00
	s_addc_u32 s21, s93, 0
	s_add_u32 s22, s92, 0x217c0c00
	s_addc_u32 s23, s93, 0
	s_add_u32 s24, s92, 0x217c0d00
	s_addc_u32 s25, s93, 0
	s_add_u32 s26, s92, 0x217c0e00
	s_addc_u32 s27, s93, 0
	s_add_u32 s28, s92, 0x217c0f00
	s_addc_u32 s29, s93, 0
	s_add_u32 s30, s92, 0x217c1000
	s_addc_u32 s31, s93, 0
	s_add_u32 s34, s92, 0x217c1100
	s_addc_u32 s35, s93, 0
	s_add_u32 s36, s92, 0x217c1200
	s_addc_u32 s37, s93, 0
	s_mul_i32 s3, s95, s54
	s_add_u32 s38, s92, 0x217c1300
	s_mul_i32 s3, s3, s94
	s_addc_u32 s39, s93, 0
	s_mov_b32 s46, 1
	s_branch .LBB0_746

; template <int PH> __global__ void __launch_bounds__(512, 2) k_phase(Params p) { run_phase<PH>(p); }
; __global__ void __launch_bounds__(512, 2) k_mega(Params p) {
	.amdhsa_kernel _Z6k_mega6Params
		.amdhsa_group_segment_fixed_size 8208
		.amdhsa_private_segment_fixed_size 0
		.amdhsa_kernarg_size 520
		.amdhsa_user_sgpr_count 2
		.amdhsa_user_sgpr_dispatch_ptr 0
		.amdhsa_user_sgpr_queue_ptr 0
		.amdhsa_user_sgpr_kernarg_segment_ptr 1
		.amdhsa_user_sgpr_dispatch_id 0
		.amdhsa_user_sgpr_kernarg_preload_length 0
		.amdhsa_user_sgpr_kernarg_preload_offset 0
		.amdhsa_user_sgpr_private_segment_size 0
		.amdhsa_uses_dynamic_stack 0
		.amdhsa_enable_private_segment 0
		.amdhsa_system_sgpr_workgroup_id_x 1
		.amdhsa_system_sgpr_workgroup_id_y 0
		.amdhsa_system_sgpr_workgroup_id_z 0
		.amdhsa_system_sgpr_workgroup_info 0
		.amdhsa_system_vgpr_workitem_id 2
		.amdhsa_next_free_vgpr 255
		.amdhsa_next_free_sgpr 98
		.amdhsa_accum_offset 256
		.amdhsa_reserve_vcc 1
		.amdhsa_float_round_mode_32 0
		.amdhsa_float_round_mode_16_64 0
		.amdhsa_float_denorm_mode_32 3
		.amdhsa_float_denorm_mode_16_64 3
		.amdhsa_dx10_clamp 1
		.amdhsa_ieee_mode 1
		.amdhsa_fp16_overflow 0
		.amdhsa_tg_split 0
		.amdhsa_exception_fp_ieee_invalid_op 0
		.amdhsa_exception_fp_denorm_src 0
		.amdhsa_exception_fp_ieee_div_zero 0
		.amdhsa_exception_fp_ieee_overflow 0
		.amdhsa_exception_fp_ieee_underflow 0
		.amdhsa_exception_fp_ieee_inexact 0
		.amdhsa_exception_int_div_zero 0
	.end_amdhsa_kernel

; template <int PH> __global__ void __launch_bounds__(512, 2) k_phase(Params p) { run_phase<PH>(p); }
; __global__ void __launch_bounds__(512, 2) k_mega(Params p) {
amdhsa.kernels:
  - .agpr_count:     0
    .args:
      - .offset:         0
        .size:           264
        .value_kind:     by_value
      - .offset:         264
        .size:           4
        .value_kind:     hidden_block_count_x
      - .offset:         268
        .size:           4
        .value_kind:     hidden_block_count_y
      - .offset:         272
        .size:           4
        .value_kind:     hidden_block_count_z
      - .offset:         276
        .size:           2
        .value_kind:     hidden_group_size_x
      - .offset:         278
        .size:           2
        .value_kind:     hidden_group_size_y
      - .offset:         280
        .size:           2
        .value_kind:     hidden_group_size_z
      - .offset:         282
        .size:           2
        .value_kind:     hidden_remainder_x
      - .offset:         284
        .size:           2
        .value_kind:     hidden_remainder_y
      - .offset:         286
        .size:           2
        .value_kind:     hidden_remainder_z
      - .offset:         304
        .size:           8
        .value_kind:     hidden_global_offset_x
      - .offset:         312
        .size:           8
        .value_kind:     hidden_global_offset_y
      - .offset:         320
        .size:           8
        .value_kind:     hidden_global_offset_z
      - .offset:         328
        .size:           2
        .value_kind:     hidden_grid_dims
      - .offset:         352
        .size:           8
        .value_kind:     hidden_multigrid_sync_arg
      - .offset:         384
        .size:           4
        .value_kind:     hidden_dynamic_lds_size
    .group_segment_fixed_size: 8208
    .kernarg_segment_align: 8
    .kernarg_segment_size: 520
    .language:       OpenCL C
    .language_version:
      - 2
      - 0
    .max_flat_workgroup_size: 512
    .name:           _Z6k_mega6Params
    .private_segment_fixed_size: 0
    .sgpr_count:     104
    .sgpr_spill_count: 20
    .symbol:         _Z6k_mega6Params.kd
    .uniform_work_group_size: 1
    .uses_dynamic_stack: false
    .vgpr_count:     255
    .vgpr_spill_count: 0
    .wavefront_size: 64
